# strategy 8: attention S^T fragment reads of batch t+1 issued before the MFMA chain of batch t (on v_rm_m1)
# baseline (speedup 1.0000x reference)
.Lattn_join:
	v_and_b32_e32 v177, 0xffff0000, v90
	v_and_b32_e32 v179, 0xffff0000, v91
	v_add_f32_e32 v94, v94, v176
	v_lshlrev_b32_e32 v176, 16, v90
	v_lshlrev_b32_e32 v178, 16, v91
	v_mul_f32_e32 v183, v177, v177
	v_mul_f32_e32 v184, v179, v179
	v_and_b32_e32 v181, 0xffff0000, v92
	v_and_b32_e32 v186, 0xffff0000, v93
	v_fmac_f32_e32 v183, v176, v176
	v_fmac_f32_e32 v184, v178, v178
	v_lshlrev_b32_e32 v180, 16, v92
	v_lshlrev_b32_e32 v182, 16, v93
	v_add_f32_e32 v183, v183, v184
	v_mul_f32_e32 v184, v181, v181
	v_mul_f32_e32 v185, v186, v186
	v_fmac_f32_e32 v184, v180, v180
	v_fmac_f32_e32 v185, v182, v182
	v_add_f32_e32 v184, v184, v185
	v_add_f32_e32 v183, v183, v184
	v_add_f32_e32 v94, v94, v183
	v_mov_b32_e32 v183, v94
	s_nop 1
	v_permlane16_swap_b32_e32 v94, v183
	v_add_f32_e32 v94, v94, v183
	v_mov_b32_e32 v183, v94
	s_nop 1
	v_permlane32_swap_b32_e32 v94, v183
	v_add_f32_e32 v94, v94, v183
	v_fmamk_f32 v94, v94, 0x3c000000, v236
	v_rsq_f32_e32 v94, v94
	s_waitcnt lgkmcnt(0)
	s_barrier
	v_mul_f32_e32 v187, 0x3e0293ee, v94
	v_mul_f32_e32 v3, v187, v3
	v_mul_f32_e32 v2, v187, v2
	v_mul_f32_e32 v3, v15, v3
	v_mul_f32_e32 v2, v14, v2
	v_cvt_pk_bf16_f32 v94, v2, v3
	v_mul_f32_e32 v3, v187, v95
	v_mul_f32_e32 v2, v187, v5
	v_mul_f32_e32 v3, v17, v3
	v_mul_f32_e32 v2, v16, v2
	v_cvt_pk_bf16_f32 v95, v2, v3
	v_mul_f32_e32 v3, v187, v97
	v_mul_f32_e32 v2, v187, v96
	v_mul_f32_e32 v3, v19, v3
	v_mul_f32_e32 v2, v18, v2
	v_cvt_pk_bf16_f32 v96, v2, v3
	v_mul_f32_e32 v3, v187, v99
	v_mul_f32_e32 v2, v187, v98
	v_mul_f32_e32 v3, v21, v3
	v_mul_f32_e32 v2, v20, v2
	v_cvt_pk_bf16_f32 v97, v2, v3
	v_mul_f32_e32 v3, v187, v101
	v_mul_f32_e32 v2, v187, v100
	v_mul_f32_e32 v3, v23, v3
	v_mul_f32_e32 v2, v22, v2
	v_cvt_pk_bf16_f32 v98, v2, v3
	v_mul_f32_e32 v3, v187, v163
	v_mul_f32_e32 v2, v187, v162
	v_mul_f32_e32 v3, v25, v3
	v_mul_f32_e32 v2, v24, v2
	v_cvt_pk_bf16_f32 v99, v2, v3
	v_mul_f32_e32 v3, v187, v165
	v_mul_f32_e32 v2, v187, v164
	v_mul_f32_e32 v3, v27, v3
	v_mul_f32_e32 v2, v26, v2
	v_cvt_pk_bf16_f32 v100, v2, v3
	v_mul_f32_e32 v3, v187, v167
	v_mul_f32_e32 v2, v187, v166
	v_mul_f32_e32 v3, v29, v3
	v_mul_f32_e32 v2, v28, v2
	v_cvt_pk_bf16_f32 v101, v2, v3
	v_mul_f32_e32 v3, v187, v169
	v_mul_f32_e32 v2, v187, v168
	v_mul_f32_e32 v3, v31, v3
	v_mul_f32_e32 v2, v30, v2
	v_cvt_pk_bf16_f32 v162, v2, v3
	v_mul_f32_e32 v3, v187, v171
	v_mul_f32_e32 v2, v187, v170
	v_mul_f32_e32 v3, v33, v3
	v_mul_f32_e32 v2, v32, v2
	v_cvt_pk_bf16_f32 v163, v2, v3
	v_mul_f32_e32 v3, v187, v173
	v_mul_f32_e32 v2, v187, v172
	v_mul_f32_e32 v3, v35, v3
	v_mul_f32_e32 v2, v34, v2
	v_cvt_pk_bf16_f32 v164, v2, v3
	v_mul_f32_e32 v3, v187, v175
	v_mul_f32_e32 v2, v187, v174
	v_mul_f32_e32 v3, v37, v3
	v_mul_f32_e32 v2, v36, v2
	v_cvt_pk_bf16_f32 v165, v2, v3
	v_mul_f32_e32 v3, v187, v177
	v_mul_f32_e32 v2, v187, v176
	v_mul_f32_e32 v3, v39, v3
	v_mul_f32_e32 v2, v38, v2
	v_cvt_pk_bf16_f32 v166, v2, v3
	v_mul_f32_e32 v3, v187, v179
	v_mul_f32_e32 v2, v187, v178
	v_mul_f32_e32 v3, v41, v3
	v_mul_f32_e32 v2, v40, v2
	v_cvt_pk_bf16_f32 v167, v2, v3
	v_mul_f32_e32 v3, v187, v181
	v_mul_f32_e32 v2, v187, v180
	v_mul_f32_e32 v3, v43, v3
	v_mul_f32_e32 v2, v42, v2
	v_cvt_pk_bf16_f32 v168, v2, v3
	v_add_u32_e32 v3, s61, v161
	v_and_or_b32 v3, v3, s33, v143
	v_lshl_add_u32 v3, v3, 8, 0
	v_add_u32_e32 v5, v3, v126
	v_add_u32_e32 v169, v3, v127
	ds_read_b128 v[170:173], v5
	ds_read_b128 v[46:49], v169
	v_add_u32_e32 v5, v3, v128
	v_mul_f32_e32 v2, v187, v182
	v_add_u32_e32 v3, v3, v129
	ds_read_b128 v[50:53], v5
	ds_read_b128 v[54:57], v3
	s_lshl_b32 s50, s55, s58
	v_mul_f32_e32 v3, v187, v186
	s_add_i32 s52, s50, s56
	v_mul_f32_e32 v2, v44, v2
	v_mul_f32_e32 v3, v45, v3
	s_add_i32 s55, s55, 1
	v_cvt_pk_bf16_f32 v169, v2, v3
	v_add_u32_e32 v2, s61, v160
	v_and_or_b32 v2, v2, s33, v144
	v_lshl_add_u32 v2, v2, 8, 0
	v_add_u32_e32 v3, v2, v126
	v_add_u32_e32 v5, v2, v127
	ds_read_b128 v[174:177], v3
	ds_read_b128 v[58:61], v5
	v_add_u32_e32 v3, v2, v128
	v_add_u32_e32 v2, v2, v129
	ds_read_b128 v[62:65], v3
	ds_read_b128 v[66:69], v2
	s_setprio 1
	s_waitcnt lgkmcnt(7)
	v_mfma_f32_16x16x32_bf16 v[170:173], v[170:173], v[94:97], 0
	s_waitcnt lgkmcnt(6)
	v_mfma_f32_16x16x32_bf16 v[170:173], v[46:49], v[98:101], v[170:173]
	s_waitcnt lgkmcnt(5)
	v_mfma_f32_16x16x32_bf16 v[170:173], v[50:53], v[162:165], v[170:173]
	s_waitcnt lgkmcnt(4)
	v_mfma_f32_16x16x32_bf16 v[170:173], v[54:57], v[166:169], v[170:173]
	s_setprio 0
	v_add_u32_e32 v2, s61, v159
	v_and_or_b32 v2, v2, s33, v145
	v_lshl_add_u32 v2, v2, 8, 0
	v_add_u32_e32 v3, v2, v126
	v_add_u32_e32 v5, v2, v127
	ds_read_b128 v[178:181], v3
	ds_read_b128 v[46:49], v5
	v_add_u32_e32 v3, v2, v128
	v_add_u32_e32 v2, v2, v129
	ds_read_b128 v[50:53], v3
	ds_read_b128 v[54:57], v2
	s_setprio 1
	s_waitcnt lgkmcnt(7)
	v_mfma_f32_16x16x32_bf16 v[174:177], v[174:177], v[94:97], 0
	s_waitcnt lgkmcnt(6)
	v_mfma_f32_16x16x32_bf16 v[174:177], v[58:61], v[98:101], v[174:177]
	s_waitcnt lgkmcnt(5)
	v_mfma_f32_16x16x32_bf16 v[174:177], v[62:65], v[162:165], v[174:177]
	s_waitcnt lgkmcnt(4)
	v_mfma_f32_16x16x32_bf16 v[174:177], v[66:69], v[166:169], v[174:177]
	s_setprio 0
	v_add_u32_e32 v2, s61, v158
	v_and_or_b32 v2, v2, s33, v146
	v_lshl_add_u32 v2, v2, 8, 0
	v_add_u32_e32 v3, v2, v126
	v_add_u32_e32 v5, v2, v127
	ds_read_b128 v[74:77], v3
	ds_read_b128 v[58:61], v5
	v_add_u32_e32 v3, v2, v128
	v_add_u32_e32 v2, v2, v129
	ds_read_b128 v[62:65], v3
	ds_read_b128 v[66:69], v2
	s_setprio 1
	s_waitcnt lgkmcnt(7)
	v_mfma_f32_16x16x32_bf16 v[178:181], v[178:181], v[94:97], 0
	s_waitcnt lgkmcnt(6)
	v_mfma_f32_16x16x32_bf16 v[178:181], v[46:49], v[98:101], v[178:181]
	s_waitcnt lgkmcnt(5)
	v_mfma_f32_16x16x32_bf16 v[178:181], v[50:53], v[162:165], v[178:181]
	s_waitcnt lgkmcnt(4)
	v_mfma_f32_16x16x32_bf16 v[178:181], v[54:57], v[166:169], v[178:181]
	s_setprio 0
	v_add_u32_e32 v2, s61, v157
	v_and_or_b32 v2, v2, s33, v147
	v_lshl_add_u32 v2, v2, 8, 0
	v_add_u32_e32 v3, v2, v126
	v_add_u32_e32 v5, v2, v127
	ds_read_b128 v[70:73], v3
	ds_read_b128 v[46:49], v5
	v_add_u32_e32 v3, v2, v128
	v_add_u32_e32 v2, v2, v129
	ds_read_b128 v[50:53], v3
	ds_read_b128 v[54:57], v2
	s_setprio 1
	s_waitcnt lgkmcnt(7)
	v_mfma_f32_16x16x32_bf16 v[74:77], v[74:77], v[94:97], 0
	s_waitcnt lgkmcnt(6)
	v_mfma_f32_16x16x32_bf16 v[74:77], v[58:61], v[98:101], v[74:77]
	s_waitcnt lgkmcnt(5)
	v_mfma_f32_16x16x32_bf16 v[74:77], v[62:65], v[162:165], v[74:77]
	s_waitcnt lgkmcnt(4)
	v_mfma_f32_16x16x32_bf16 v[192:195], v[66:69], v[166:169], v[74:77]
	s_setprio 0
	v_add_u32_e32 v2, s61, v156
	v_and_or_b32 v2, v2, s33, v148
	v_lshl_add_u32 v2, v2, 8, 0
	v_add_u32_e32 v3, v2, v126
	v_add_u32_e32 v5, v2, v127
	ds_read_b128 v[74:77], v3
	ds_read_b128 v[58:61], v5
	v_add_u32_e32 v3, v2, v128
	v_add_u32_e32 v2, v2, v129
	ds_read_b128 v[62:65], v3
	ds_read_b128 v[66:69], v2
	s_setprio 1
	s_waitcnt lgkmcnt(7)
	v_mfma_f32_16x16x32_bf16 v[70:73], v[70:73], v[94:97], 0
	s_waitcnt lgkmcnt(6)
	v_mfma_f32_16x16x32_bf16 v[70:73], v[46:49], v[98:101], v[70:73]
	s_waitcnt lgkmcnt(5)
	v_mfma_f32_16x16x32_bf16 v[70:73], v[50:53], v[162:165], v[70:73]
	s_waitcnt lgkmcnt(4)
	v_mfma_f32_16x16x32_bf16 v[196:199], v[54:57], v[166:169], v[70:73]
	s_setprio 0
	v_add_u32_e32 v2, s61, v155
	v_and_or_b32 v2, v2, s33, v149
	v_lshl_add_u32 v2, v2, 8, 0
	v_add_u32_e32 v3, v2, v126
	v_add_u32_e32 v5, v2, v127
	ds_read_b128 v[70:73], v3
	ds_read_b128 v[46:49], v5
	v_add_u32_e32 v3, v2, v128
	v_add_u32_e32 v2, v2, v129
	ds_read_b128 v[50:53], v3
	ds_read_b128 v[54:57], v2
	s_setprio 1
	s_waitcnt lgkmcnt(7)
	v_mfma_f32_16x16x32_bf16 v[74:77], v[74:77], v[94:97], 0
	s_waitcnt lgkmcnt(6)
	v_mfma_f32_16x16x32_bf16 v[74:77], v[58:61], v[98:101], v[74:77]
	s_waitcnt lgkmcnt(5)
	v_mfma_f32_16x16x32_bf16 v[74:77], v[62:65], v[162:165], v[74:77]
	s_waitcnt lgkmcnt(4)
	v_mfma_f32_16x16x32_bf16 v[200:203], v[66:69], v[166:169], v[74:77]
	s_setprio 0
	v_add_u32_e32 v2, s61, v154
	v_and_or_b32 v2, v2, s33, v150
	v_lshl_add_u32 v2, v2, 8, 0
	v_add_u32_e32 v3, v2, v126
	v_add_u32_e32 v5, v2, v127
	ds_read_b128 v[74:77], v3
	ds_read_b128 v[58:61], v5
	v_add_u32_e32 v3, v2, v128
	v_add_u32_e32 v2, v2, v129
	ds_read_b128 v[62:65], v3
	ds_read_b128 v[66:69], v2
	s_setprio 1
	s_waitcnt lgkmcnt(7)
	v_mfma_f32_16x16x32_bf16 v[70:73], v[70:73], v[94:97], 0
	s_waitcnt lgkmcnt(6)
	v_mfma_f32_16x16x32_bf16 v[70:73], v[46:49], v[98:101], v[70:73]
	s_waitcnt lgkmcnt(5)
	v_mfma_f32_16x16x32_bf16 v[70:73], v[50:53], v[162:165], v[70:73]
	s_waitcnt lgkmcnt(4)
	v_mfma_f32_16x16x32_bf16 v[204:207], v[54:57], v[166:169], v[70:73]
	s_setprio 0
	v_add_u32_e32 v2, s61, v153
	v_and_or_b32 v2, v2, s33, v151
	v_lshl_add_u32 v2, v2, 8, 0
	v_add_u32_e32 v3, v2, v126
	v_add_u32_e32 v5, v2, v127
	ds_read_b128 v[70:73], v3
	ds_read_b128 v[46:49], v5
	v_add_u32_e32 v3, v2, v128
	v_add_u32_e32 v2, v2, v129
	ds_read_b128 v[50:53], v3
	ds_read_b128 v[54:57], v2
	s_setprio 1
	s_waitcnt lgkmcnt(7)
	v_mfma_f32_16x16x32_bf16 v[74:77], v[74:77], v[94:97], 0
	s_waitcnt lgkmcnt(6)
	v_mfma_f32_16x16x32_bf16 v[74:77], v[58:61], v[98:101], v[74:77]
	s_waitcnt lgkmcnt(5)
	v_mfma_f32_16x16x32_bf16 v[74:77], v[62:65], v[162:165], v[74:77]
	s_waitcnt lgkmcnt(4)
	v_mfma_f32_16x16x32_bf16 v[208:211], v[66:69], v[166:169], v[74:77]
	s_setprio 0
	s_setprio 1
	s_waitcnt lgkmcnt(3)
	v_mfma_f32_16x16x32_bf16 v[94:97], v[70:73], v[94:97], 0
	s_waitcnt lgkmcnt(2)
	v_mfma_f32_16x16x32_bf16 v[94:97], v[46:49], v[98:101], v[94:97]
	s_waitcnt lgkmcnt(1)
	v_mfma_f32_16x16x32_bf16 v[94:97], v[50:53], v[162:165], v[94:97]
	s_waitcnt lgkmcnt(0)
	v_mfma_f32_16x16x32_bf16 v[94:97], v[54:57], v[166:169], v[94:97]
	s_setprio 0
	s_cmp_eq_u32 s60, 0
	v_exp_f32_e32 v2, v170
	s_cselect_b64 s[50:51], -1, 0
	v_exp_f32_e32 v3, v171
	s_and_b64 s[64:65], s[14:15], s[50:51]
	s_or_b64 s[66:67], s[64:65], s[12:13]
	v_cndmask_b32_e64 v99, v2, 0, s[66:67]
	s_or_b64 s[66:67], s[64:65], s[16:17]
	v_cndmask_b32_e64 v163, v3, 0, s[66:67]
	v_exp_f32_e32 v3, v172
	v_exp_f32_e32 v5, v173
	s_or_b64 s[66:67], s[64:65], s[18:19]
	s_or_b64 s[64:65], s[64:65], s[20:21]
	v_cndmask_b32_e64 v165, v3, 0, s[66:67]
	v_exp_f32_e32 v3, v174
	v_cndmask_b32_e64 v169, v5, 0, s[64:65]
	v_exp_f32_e32 v5, v175
	s_and_b64 s[64:65], s[22:23], s[50:51]
	v_cndmask_b32_e64 v187, v3, 0, s[64:65]
	v_exp_f32_e32 v3, v176
	v_cndmask_b32_e64 v188, v5, 0, s[64:65]
	v_exp_f32_e32 v5, v177
	v_add_f32_e32 v2, 0, v99
	v_cndmask_b32_e64 v189, v3, 0, s[64:65]
	v_exp_f32_e32 v3, v178
	v_cndmask_b32_e64 v190, v5, 0, s[64:65]
	v_exp_f32_e32 v5, v179
	s_and_b64 s[64:65], s[24:25], s[50:51]
	v_cndmask_b32_e64 v179, v3, 0, s[64:65]
	v_exp_f32_e32 v3, v180
	v_cndmask_b32_e64 v180, v5, 0, s[64:65]
	v_exp_f32_e32 v5, v181
	v_add_f32_e32 v2, v163, v2
	v_cndmask_b32_e64 v181, v3, 0, s[64:65]
	v_exp_f32_e32 v3, v192
	v_cndmask_b32_e64 v182, v5, 0, s[64:65]
	v_exp_f32_e32 v5, v193
	s_and_b64 s[64:65], s[26:27], s[50:51]
	v_cndmask_b32_e64 v183, v3, 0, s[64:65]
	v_exp_f32_e32 v3, v194
	v_cndmask_b32_e64 v184, v5, 0, s[64:65]
	v_exp_f32_e32 v5, v195
	v_add_f32_e32 v2, v165, v2
	v_cndmask_b32_e64 v185, v3, 0, s[64:65]
	v_exp_f32_e32 v3, v196
	v_cndmask_b32_e64 v186, v5, 0, s[64:65]
	v_exp_f32_e32 v5, v197
	s_and_b64 s[64:65], s[28:29], s[50:51]
	v_cndmask_b32_e64 v171, v3, 0, s[64:65]
	v_exp_f32_e32 v3, v198
	v_cndmask_b32_e64 v172, v5, 0, s[64:65]
	v_exp_f32_e32 v5, v199
	v_add_f32_e32 v2, v169, v2
	v_add_f32_e32 v2, v2, v187
	v_add_f32_e32 v2, v188, v2
	v_cndmask_b32_e64 v173, v3, 0, s[64:65]
	v_exp_f32_e32 v3, v200
	v_add_f32_e32 v2, v189, v2
	v_cndmask_b32_e64 v174, v5, 0, s[64:65]
	v_exp_f32_e32 v5, v201
	v_add_f32_e32 v2, v190, v2
	v_add_f32_e32 v2, v2, v179
	s_and_b64 s[64:65], s[30:31], s[50:51]
	v_add_f32_e32 v2, v180, v2
	v_cndmask_b32_e64 v175, v3, 0, s[64:65]
	v_exp_f32_e32 v3, v202
	v_add_f32_e32 v2, v181, v2
	v_cndmask_b32_e64 v176, v5, 0, s[64:65]
	v_exp_f32_e32 v5, v203
	v_add_f32_e32 v2, v182, v2
	v_add_f32_e32 v2, v2, v183
	v_add_f32_e32 v2, v184, v2
	v_cndmask_b32_e64 v177, v3, 0, s[64:65]
	v_exp_f32_e32 v3, v204
	v_add_f32_e32 v2, v185, v2
	v_cndmask_b32_e64 v178, v5, 0, s[64:65]
	v_exp_f32_e32 v5, v205
	v_add_f32_e32 v2, v186, v2
	v_add_f32_e32 v2, v2, v171
	s_and_b64 s[64:65], s[34:35], s[50:51]
	v_add_f32_e32 v2, v172, v2
	v_cndmask_b32_e64 v100, v3, 0, s[64:65]
	v_exp_f32_e32 v3, v206
	v_add_f32_e32 v2, v173, v2
	v_cndmask_b32_e64 v101, v5, 0, s[64:65]
	v_exp_f32_e32 v5, v207
	v_add_f32_e32 v2, v174, v2
	v_add_f32_e32 v2, v2, v175
	v_add_f32_e32 v2, v176, v2
	v_cndmask_b32_e64 v162, v3, 0, s[64:65]
	v_exp_f32_e32 v3, v208
	v_add_f32_e32 v2, v177, v2
	v_cndmask_b32_e64 v164, v5, 0, s[64:65]
	v_exp_f32_e32 v5, v209
	v_add_f32_e32 v2, v178, v2
	v_add_f32_e32 v2, v2, v100
	s_and_b64 s[64:65], s[36:37], s[50:51]
	v_add_f32_e32 v2, v101, v2
	v_cndmask_b32_e64 v166, v3, 0, s[64:65]
	v_exp_f32_e32 v3, v210
	v_add_f32_e32 v2, v162, v2
	v_cndmask_b32_e64 v167, v5, 0, s[64:65]
	v_exp_f32_e32 v5, v211
	v_add_f32_e32 v2, v164, v2
	v_add_f32_e32 v2, v2, v166
	v_add_f32_e32 v2, v167, v2
	v_cndmask_b32_e64 v168, v3, 0, s[64:65]
	v_add_f32_e32 v2, v168, v2
	v_cndmask_b32_e64 v170, v5, 0, s[64:65]
	v_add_f32_e32 v3, v170, v2
	v_exp_f32_e32 v2, v94
	v_exp_f32_e32 v5, v95
	s_and_b64 s[50:51], s[38:39], s[50:51]
	s_or_b64 s[64:65], s[50:51], s[10:11]
	v_cndmask_b32_e64 v2, v2, 0, s[64:65]
	s_or_b64 s[64:65], s[50:51], s[40:41]
	v_add_f32_e32 v94, v3, v2
	v_cndmask_b32_e64 v3, v5, 0, s[64:65]
	v_exp_f32_e32 v5, v96
	v_exp_f32_e32 v95, v97
	s_or_b64 s[64:65], s[50:51], s[42:43]
	v_add_f32_e32 v94, v3, v94
	v_cndmask_b32_e64 v5, v5, 0, s[64:65]
	s_or_b64 s[50:51], s[50:51], s[44:45]
	v_add_f32_e32 v94, v5, v94
	v_cndmask_b32_e64 v98, v95, 0, s[50:51]
	v_add_f32_e32 v94, v98, v94
	v_mov_b32_e32 v95, v94
	s_nop 1
	v_permlane16_swap_b32_e32 v94, v95
	v_add_f32_e32 v96, v94, v95
	s_cmp_lt_u32 s55, s59
	v_mov_b32_e32 v97, v96
	s_cselect_b64 s[50:51], -1, 0
	s_cmp_ge_u32 s55, s59
	v_permlane32_swap_b32_e32 v96, v97
	s_cbranch_scc1 .LBB0_587
	s_add_i32 s53, s52, s57
	s_ashr_i32 s63, s53, 31
	s_add_u32 s64, s46, s53
	s_addc_u32 s65, s47, s63
	v_lshl_add_u64 v[46:47], s[64:65], 0, v[110:111]
	v_lshl_add_u64 v[54:55], s[64:65], 0, v[112:113]
	v_lshl_add_u64 v[62:63], s[64:65], 0, v[114:115]
	v_lshl_add_u64 v[70:71], s[64:65], 0, v[116:117]
	v_lshl_add_u64 v[78:79], s[64:65], 0, v[118:119]
	v_mad_u64_u32 v[50:51], s[66:67], v46, s77, v[108:109]
	v_mad_u64_u32 v[58:59], s[66:67], v54, s77, v[108:109]
	v_mad_u64_u32 v[66:67], s[66:67], v62, s77, v[108:109]
	v_mad_u64_u32 v[74:75], s[66:67], v70, s77, v[108:109]
	v_mad_u64_u32 v[90:91], s[64:65], v78, s77, v[104:105]
	v_mad_i32_i24 v51, v47, s77, v51
	v_mad_i32_i24 v59, v55, s77, v59
	v_mad_i32_i24 v67, v63, s77, v67
	v_mad_i32_i24 v75, v71, s77, v75
	v_mad_i32_i24 v91, v79, s77, v91
	global_load_dwordx4 v[46:49], v[50:51], off offset:1024
	s_nop 0
	global_load_dwordx4 v[50:53], v[50:51], off offset:2048
	s_nop 0
	global_load_dwordx4 v[54:57], v[58:59], off offset:1024
	s_nop 0
	global_load_dwordx4 v[58:61], v[58:59], off offset:2048
	s_nop 0
	global_load_dwordx4 v[62:65], v[66:67], off offset:1024
	s_nop 0
	global_load_dwordx4 v[66:69], v[66:67], off offset:2048
	s_nop 0
	global_load_dwordx4 v[70:73], v[74:75], off offset:1024
	s_nop 0
	global_load_dwordx4 v[74:77], v[74:75], off offset:2048
	s_nop 0
	global_load_dwordx4 v[78:81], v[90:91], off
	global_load_dwordx4 v[82:85], v[90:91], off offset:64
	global_load_dwordx4 v[86:89], v[90:91], off offset:128
	s_nop 0
	global_load_dwordx4 v[90:93], v[90:91], off offset:192
